# v40 + attention tile-head LDS-DMA issue straight-lined (8 always-taken piece branches + out-of-line blocks removed, alternating address temps)
# baseline (speedup 1.0000x reference)
.LBB0_699:
	s_waitcnt vmcnt(0)
	s_add_i32 s60, s50, 1
	s_cmp_ge_i32 s60, s28
	s_waitcnt lgkmcnt(0)
	s_barrier
	s_cbranch_scc1 .LBB0_710
	s_bitcmp1_b32 s60, 0
	s_cselect_b32 s0, 0x11800, 0
	s_add_i32 s1, s45, s50
	v_mad_i64_i32 v[2:3], s[2:3], s1, v252, v[196:197]
	s_add_i32 s1, s0, s80
	v_lshl_add_u64 v[172:173], v[2:3], 0, s[80:81]
	s_mov_b32 m0, s1
	v_lshl_add_u64 v[174:175], v[2:3], 0, s[92:93]
	global_load_lds_dwordx4 v[172:173], off
	s_add_i32 m0, s1, 0x2000
	v_lshl_add_u64 v[172:173], v[2:3], 0, s[24:25]
	global_load_lds_dwordx4 v[174:175], off
	s_add_i32 m0, s1, 0x4000
	v_lshl_add_u64 v[174:175], v[2:3], 0, s[84:85]
	global_load_lds_dwordx4 v[172:173], off
	s_add_i32 m0, s1, 0x6000
	v_lshl_add_u64 v[172:173], v[2:3], 0, s[94:95]
	global_load_lds_dwordx4 v[174:175], off
	s_add_i32 m0, s1, 0x8000
	v_lshl_add_u64 v[174:175], v[2:3], 0, s[48:49]
	global_load_lds_dwordx4 v[172:173], off
	s_add_i32 m0, s1, 0xa000
	v_lshl_add_u64 v[172:173], v[2:3], 0, s[56:57]
	global_load_lds_dwordx4 v[174:175], off
	s_add_i32 m0, s1, 0xc000
	v_lshl_add_u64 v[174:175], v[2:3], 0, s[66:67]
	global_load_lds_dwordx4 v[172:173], off
	s_add_i32 m0, s1, 0xe000
	s_and_b64 vcc, exec, s[22:23]
	global_load_lds_dwordx4 v[174:175], off
	s_cbranch_vccnz .LBB0_710

.LBB0_724:
	s_cmp_eq_u32 s28, s60
	s_cbranch_scc1 .LBB0_734
	s_mov_b32 s50, s60
	s_branch .LBB0_699
.LBB0_734:
	s_mov_b32 s60, 0x1e402000
